# Hyena hidden matrix stored j-quad-major [16][4096][4] so the filter-generation loads are fully coalesced (64 consecutive t per dwordx4) instead of one 256-B row per lane
# speedup vs baseline: 1.0060x; 1.0060x over previous
; __device__ __forceinline__ void hy_hdn_row(const float* w1, const float* b1, const float* fq, const float* w2, const float* b2, float* hdn2, int t, int lane) {
;     ...
; #pragma unroll 1
;     for (int i0 = 0; i0 < 64; i0 += 16) { float wv[16];
; #pragma unroll
;         for (int i = 0; i < 16; ++i) wv[i] = w2[(i0 + i) * 64 + lane];
; #pragma unroll
;         for (int i = 0; i < 16; ++i) pre2 += __shfl(h1, i0 + i) * wv[i]; }
;     hdn2[t * 64 + lane] = sinf(f * pre2);
.LBB0_143:
	s_or_b64 exec, exec, s[4:5]
	v_mul_f32_e32 v50, v49, v49
	v_fmamk_f32 v51, v50, 0xb94c1982, v217
	v_fmaak_f32 v51, v50, v51, 0xbe2aaa9d
	v_mul_f32_e32 v51, v50, v51
	v_fmac_f32_e32 v49, v49, v51
	v_fmamk_f32 v51, v50, 0x37d75334, v218
	v_fmaak_f32 v51, v50, v51, 0x3d2aabf7
	v_fmaak_f32 v51, v50, v51, 0xbf000004
	v_fma_f32 v50, v50, v51, 1.0
	v_and_b32_e32 v51, 1, v48
	v_lshlrev_b32_e32 v48, 30, v48
	v_cmp_eq_u32_e32 vcc, 0, v51
	v_and_b32_e32 v48, 0x80000000, v48
	v_xor_b32_e32 v45, v45, v44
	v_cndmask_b32_e32 v49, v50, v49, vcc
	v_xor_b32_e32 v45, v45, v48
	v_xor_b32_e32 v45, v45, v49
	v_cmp_class_f32_e64 vcc, v44, s23
	v_lshrrev_b32_e32 v44, 2, v46
	v_readlane_b32 s4, v254, 12
	v_cndmask_b32_e32 v48, v222, v45, vcc
	v_and_b32_e32 v45, 3, v46
	v_lshl_or_b32 v44, v44, 14, v45
	v_lshl_or_b32 v44, s52, 2, v44
	v_mov_b32_e32 v45, 0
	s_add_i32 s52, s52, s4
	v_lshl_add_u64 v[44:45], v[44:45], 2, s[0:1]
	s_cmpk_lt_i32 s52, 0x1000
	global_store_dword v[44:45], v48, off
	s_cbranch_scc0 .LBB0_282

; __device__ __forceinline__ void hy_conv_item(const Ctx& C, int l, int c) {
;     ...
;     for (int k = 0; k < 8; ++k) { const int t = tid + NTHR * k; const f32x4* hr = (const f32x4*)(hdn + (size_t)t * 64);
;         float a0 = 0.f, a1 = 0.f, a2 = 0.f, a3 = 0.f;
; #pragma unroll 1
;         for (int j8 = 0; j8 < 16; j8 += 8) {
;         f32x4 hrow[8];
; #pragma unroll
;         for (int j4 = 0; j4 < 8; ++j4) hrow[j4] = hr[j8 + j4];
; #pragma unroll
;         for (int jj4 = 0; jj4 < 8; ++jj4) { const f32x4 hv = hrow[jj4]; const int j4 = j8 + jj4;
;             const f32x4 q0 = *(const f32x4*)(w3s + 4 * j4), q1 = *(const f32x4*)(w3s + 64 + 4 * j4), q2 = *(const f32x4*)(w3s + 128 + 4 * j4), q3 = *(const f32x4*)(w3s + 192 + 4 * j4);
;             a0 += hv.x * q0.x + hv.y * q0.y + hv.z * q0.z + hv.w * q0.w; a1 += hv.x * q1.x + hv.y * q1.y + hv.z * q1.z + hv.w * q1.w;
;             a2 += hv.x * q2.x + hv.y * q2.y + hv.z * q2.z + hv.w * q2.w; a3 += hv.x * q3.x + hv.y * q3.y + hv.z * q3.z + hv.w * q3.w; } }
.LBB0_612:
	v_lshl_add_u32 v8, s7, 9, v114
	v_ashrrev_i32_e32 v9, 31, v8
	v_lshlrev_b64 v[0:1], 8, v[8:9]
	v_lshl_add_u64 v[10:11], s[4:5], 0, v[0:1]
	s_mov_b64 s[0:1], -1
	s_mov_b32 s36, 0
	v_mov_b32_e32 v14, 0
	v_mov_b32_e32 v15, v17
	v_mov_b32_e32 v12, 0
	v_mov_b32_e32 v13, v17
	v_lshlrev_b32_e32 v0, 4, v8
	s_mov_b64 s[8:9], s[4:5]
	global_load_dwordx4 v[18:21], v0, s[8:9]
	s_add_u32 s8, s8, 0x10000
	s_addc_u32 s9, s9, 0
	global_load_dwordx4 v[22:25], v0, s[8:9]
	s_add_u32 s8, s8, 0x10000
	s_addc_u32 s9, s9, 0
	global_load_dwordx4 v[26:29], v0, s[8:9]
	s_add_u32 s8, s8, 0x10000
	s_addc_u32 s9, s9, 0
	global_load_dwordx4 v[30:33], v0, s[8:9]
	s_add_u32 s8, s8, 0x10000
	s_addc_u32 s9, s9, 0
	global_load_dwordx4 v[34:37], v0, s[8:9]
	s_add_u32 s8, s8, 0x10000
	s_addc_u32 s9, s9, 0
	global_load_dwordx4 v[38:41], v0, s[8:9]
	s_add_u32 s8, s8, 0x10000
	s_addc_u32 s9, s9, 0
	global_load_dwordx4 v[42:45], v0, s[8:9]
	s_add_u32 s8, s8, 0x10000
	s_addc_u32 s9, s9, 0
	global_load_dwordx4 v[46:49], v0, s[8:9]
	s_add_u32 s8, s8, 0x10000
	s_addc_u32 s9, s9, 0
	global_load_dwordx4 v[192:195], v0, s[8:9]
	s_add_u32 s8, s8, 0x10000
	s_addc_u32 s9, s9, 0
	global_load_dwordx4 v[196:199], v0, s[8:9]
	s_add_u32 s8, s8, 0x10000
	s_addc_u32 s9, s9, 0
	global_load_dwordx4 v[200:203], v0, s[8:9]
	s_add_u32 s8, s8, 0x10000
	s_addc_u32 s9, s9, 0
	global_load_dwordx4 v[204:207], v0, s[8:9]
	s_add_u32 s8, s8, 0x10000
	s_addc_u32 s9, s9, 0
	global_load_dwordx4 v[208:211], v0, s[8:9]
	s_add_u32 s8, s8, 0x10000
	s_addc_u32 s9, s9, 0
	global_load_dwordx4 v[212:215], v0, s[8:9]
	s_add_u32 s8, s8, 0x10000
	s_addc_u32 s9, s9, 0
	global_load_dwordx4 v[228:231], v0, s[8:9]
	s_add_u32 s8, s8, 0x10000
	s_addc_u32 s9, s9, 0
	global_load_dwordx4 v[232:235], v0, s[8:9]
	v_mov_b32_e32 v9, s61
	ds_read_b128 v[142:145], v9
	ds_read_b128 v[146:149], v9 offset:16
	ds_read_b128 v[150:153], v9 offset:32
	ds_read_b128 v[154:157], v9 offset:48
	ds_read_b128 v[158:161], v9 offset:64
	ds_read_b128 v[162:165], v9 offset:80
	ds_read_b128 v[166:169], v9 offset:96
	ds_read_b128 v[170:173], v9 offset:112
	ds_read_b128 v[174:177], v9 offset:128
	ds_read_b128 v[178:181], v9 offset:144
	ds_read_b128 v[50:53], v9 offset:160
	ds_read_b128 v[54:57], v9 offset:176
	s_waitcnt vmcnt(15) lgkmcnt(11)
	v_pk_fma_f32 v[14:15], v[18:19], v[142:143], v[14:15] op_sel_hi:[0,1,1]
	v_pk_fma_f32 v[12:13], v[18:19], v[144:145], v[12:13] op_sel_hi:[0,1,1]
	ds_read_b128 v[142:145], v9 offset:192
	s_waitcnt lgkmcnt(11)
	v_pk_mul_f32 v[58:59], v[18:19], v[146:147] op_sel:[1,0] op_sel_hi:[1,1]
	v_pk_mul_f32 v[60:61], v[18:19], v[148:149] op_sel:[1,0] op_sel_hi:[1,1]
	ds_read_b128 v[146:149], v9 offset:208
	s_waitcnt lgkmcnt(11)
	v_pk_fma_f32 v[14:15], v[20:21], v[150:151], v[14:15] op_sel_hi:[0,1,1]
	v_pk_fma_f32 v[12:13], v[20:21], v[152:153], v[12:13] op_sel_hi:[0,1,1]
	ds_read_b128 v[150:153], v9 offset:224
	s_waitcnt lgkmcnt(11)
	v_pk_fma_f32 v[58:59], v[20:21], v[154:155], v[58:59] op_sel:[1,0,0] op_sel_hi:[1,1,1]
	v_pk_fma_f32 v[60:61], v[20:21], v[156:157], v[60:61] op_sel:[1,0,0] op_sel_hi:[1,1,1]
	ds_read_b128 v[154:157], v9 offset:240
	s_waitcnt vmcnt(14) lgkmcnt(11)
	v_pk_fma_f32 v[14:15], v[22:23], v[158:159], v[14:15] op_sel_hi:[0,1,1]
	v_pk_fma_f32 v[12:13], v[22:23], v[160:161], v[12:13] op_sel_hi:[0,1,1]
	ds_read_b128 v[158:161], v9 offset:256
	s_waitcnt lgkmcnt(11)
	v_pk_fma_f32 v[58:59], v[22:23], v[162:163], v[58:59] op_sel:[1,0,0] op_sel_hi:[1,1,1]
	v_pk_fma_f32 v[60:61], v[22:23], v[164:165], v[60:61] op_sel:[1,0,0] op_sel_hi:[1,1,1]
	ds_read_b128 v[162:165], v9 offset:272
	s_waitcnt lgkmcnt(11)
	v_pk_fma_f32 v[14:15], v[24:25], v[166:167], v[14:15] op_sel_hi:[0,1,1]
	v_pk_fma_f32 v[12:13], v[24:25], v[168:169], v[12:13] op_sel_hi:[0,1,1]
	ds_read_b128 v[166:169], v9 offset:288
	s_waitcnt lgkmcnt(11)
	v_pk_fma_f32 v[58:59], v[24:25], v[170:171], v[58:59] op_sel:[1,0,0] op_sel_hi:[1,1,1]
	v_pk_fma_f32 v[60:61], v[24:25], v[172:173], v[60:61] op_sel:[1,0,0] op_sel_hi:[1,1,1]
	ds_read_b128 v[170:173], v9 offset:304
	s_waitcnt vmcnt(13) lgkmcnt(11)
	v_pk_fma_f32 v[14:15], v[26:27], v[174:175], v[14:15] op_sel_hi:[0,1,1]
	v_pk_fma_f32 v[12:13], v[26:27], v[176:177], v[12:13] op_sel_hi:[0,1,1]
	ds_read_b128 v[174:177], v9 offset:320
	s_waitcnt lgkmcnt(11)
	v_pk_fma_f32 v[58:59], v[26:27], v[178:179], v[58:59] op_sel:[1,0,0] op_sel_hi:[1,1,1]
	v_pk_fma_f32 v[60:61], v[26:27], v[180:181], v[60:61] op_sel:[1,0,0] op_sel_hi:[1,1,1]
	ds_read_b128 v[178:181], v9 offset:336
	s_waitcnt lgkmcnt(11)
	v_pk_fma_f32 v[14:15], v[28:29], v[50:51], v[14:15] op_sel_hi:[0,1,1]
	v_pk_fma_f32 v[12:13], v[28:29], v[52:53], v[12:13] op_sel_hi:[0,1,1]
	ds_read_b128 v[50:53], v9 offset:352
	s_waitcnt lgkmcnt(11)
	v_pk_fma_f32 v[58:59], v[28:29], v[54:55], v[58:59] op_sel:[1,0,0] op_sel_hi:[1,1,1]
	v_pk_fma_f32 v[60:61], v[28:29], v[56:57], v[60:61] op_sel:[1,0,0] op_sel_hi:[1,1,1]
	ds_read_b128 v[54:57], v9 offset:368
	s_waitcnt vmcnt(12) lgkmcnt(11)
	v_pk_fma_f32 v[14:15], v[30:31], v[142:143], v[14:15] op_sel_hi:[0,1,1]
	v_pk_fma_f32 v[12:13], v[30:31], v[144:145], v[12:13] op_sel_hi:[0,1,1]
	ds_read_b128 v[142:145], v9 offset:384
	s_waitcnt lgkmcnt(11)
	v_pk_fma_f32 v[58:59], v[30:31], v[146:147], v[58:59] op_sel:[1,0,0] op_sel_hi:[1,1,1]
	v_pk_fma_f32 v[60:61], v[30:31], v[148:149], v[60:61] op_sel:[1,0,0] op_sel_hi:[1,1,1]
	ds_read_b128 v[146:149], v9 offset:400
	s_waitcnt lgkmcnt(11)
	v_pk_fma_f32 v[14:15], v[32:33], v[150:151], v[14:15] op_sel_hi:[0,1,1]
	v_pk_fma_f32 v[12:13], v[32:33], v[152:153], v[12:13] op_sel_hi:[0,1,1]
	ds_read_b128 v[150:153], v9 offset:416
	s_waitcnt lgkmcnt(11)
; __device__ __forceinline__ void hy_conv_item(const Ctx& C, int l, int c) {
;     ...
;     for (int k = 0; k < 8; ++k) { const int t = tid + NTHR * k; const f32x4* hr = (const f32x4*)(hdn + (size_t)t * 64);
;         float a0 = 0.f, a1 = 0.f, a2 = 0.f, a3 = 0.f;
; #pragma unroll 1
;         for (int j8 = 0; j8 < 16; j8 += 8) {
;         f32x4 hrow[8];
; #pragma unroll
;         for (int j4 = 0; j4 < 8; ++j4) hrow[j4] = hr[j8 + j4];
; #pragma unroll
;         for (int jj4 = 0; jj4 < 8; ++jj4) { const f32x4 hv = hrow[jj4]; const int j4 = j8 + jj4;
;             const f32x4 q0 = *(const f32x4*)(w3s + 4 * j4), q1 = *(const f32x4*)(w3s + 64 + 4 * j4), q2 = *(const f32x4*)(w3s + 128 + 4 * j4), q3 = *(const f32x4*)(w3s + 192 + 4 * j4);
;             a0 += hv.x * q0.x + hv.y * q0.y + hv.z * q0.z + hv.w * q0.w; a1 += hv.x * q1.x + hv.y * q1.y + hv.z * q1.z + hv.w * q1.w;
;             a2 += hv.x * q2.x + hv.y * q2.y + hv.z * q2.z + hv.w * q2.w; a3 += hv.x * q3.x + hv.y * q3.y + hv.z * q3.z + hv.w * q3.w; } }
	v_pk_fma_f32 v[58:59], v[32:33], v[154:155], v[58:59] op_sel:[1,0,0] op_sel_hi:[1,1,1]
	v_pk_fma_f32 v[60:61], v[32:33], v[156:157], v[60:61] op_sel:[1,0,0] op_sel_hi:[1,1,1]
	ds_read_b128 v[154:157], v9 offset:432
	s_waitcnt vmcnt(11) lgkmcnt(11)
	v_pk_fma_f32 v[14:15], v[34:35], v[158:159], v[14:15] op_sel_hi:[0,1,1]
	v_pk_fma_f32 v[12:13], v[34:35], v[160:161], v[12:13] op_sel_hi:[0,1,1]
	ds_read_b128 v[158:161], v9 offset:448
	s_waitcnt lgkmcnt(11)
	v_pk_fma_f32 v[58:59], v[34:35], v[162:163], v[58:59] op_sel:[1,0,0] op_sel_hi:[1,1,1]
	v_pk_fma_f32 v[60:61], v[34:35], v[164:165], v[60:61] op_sel:[1,0,0] op_sel_hi:[1,1,1]
	ds_read_b128 v[162:165], v9 offset:464
	s_waitcnt lgkmcnt(11)
	v_pk_fma_f32 v[14:15], v[36:37], v[166:167], v[14:15] op_sel_hi:[0,1,1]
	v_pk_fma_f32 v[12:13], v[36:37], v[168:169], v[12:13] op_sel_hi:[0,1,1]
	ds_read_b128 v[166:169], v9 offset:480
	s_waitcnt lgkmcnt(11)
	v_pk_fma_f32 v[58:59], v[36:37], v[170:171], v[58:59] op_sel:[1,0,0] op_sel_hi:[1,1,1]
	v_pk_fma_f32 v[60:61], v[36:37], v[172:173], v[60:61] op_sel:[1,0,0] op_sel_hi:[1,1,1]
	ds_read_b128 v[170:173], v9 offset:496
	s_waitcnt vmcnt(10) lgkmcnt(11)
	v_pk_fma_f32 v[14:15], v[38:39], v[174:175], v[14:15] op_sel_hi:[0,1,1]
	v_pk_fma_f32 v[12:13], v[38:39], v[176:177], v[12:13] op_sel_hi:[0,1,1]
	ds_read_b128 v[174:177], v9 offset:512
	s_waitcnt lgkmcnt(11)
	v_pk_fma_f32 v[58:59], v[38:39], v[178:179], v[58:59] op_sel:[1,0,0] op_sel_hi:[1,1,1]
	v_pk_fma_f32 v[60:61], v[38:39], v[180:181], v[60:61] op_sel:[1,0,0] op_sel_hi:[1,1,1]
	ds_read_b128 v[178:181], v9 offset:528
	s_waitcnt lgkmcnt(11)
	v_pk_fma_f32 v[14:15], v[40:41], v[50:51], v[14:15] op_sel_hi:[0,1,1]
	v_pk_fma_f32 v[12:13], v[40:41], v[52:53], v[12:13] op_sel_hi:[0,1,1]
	ds_read_b128 v[50:53], v9 offset:544
	s_waitcnt lgkmcnt(11)
	v_pk_fma_f32 v[58:59], v[40:41], v[54:55], v[58:59] op_sel:[1,0,0] op_sel_hi:[1,1,1]
	v_pk_fma_f32 v[60:61], v[40:41], v[56:57], v[60:61] op_sel:[1,0,0] op_sel_hi:[1,1,1]
	ds_read_b128 v[54:57], v9 offset:560
	s_waitcnt vmcnt(9) lgkmcnt(11)
	v_pk_fma_f32 v[14:15], v[42:43], v[142:143], v[14:15] op_sel_hi:[0,1,1]
	v_pk_fma_f32 v[12:13], v[42:43], v[144:145], v[12:13] op_sel_hi:[0,1,1]
	ds_read_b128 v[142:145], v9 offset:576
	s_waitcnt lgkmcnt(11)
	v_pk_fma_f32 v[58:59], v[42:43], v[146:147], v[58:59] op_sel:[1,0,0] op_sel_hi:[1,1,1]
	v_pk_fma_f32 v[60:61], v[42:43], v[148:149], v[60:61] op_sel:[1,0,0] op_sel_hi:[1,1,1]
	ds_read_b128 v[146:149], v9 offset:592
	s_waitcnt lgkmcnt(11)
	v_pk_fma_f32 v[14:15], v[44:45], v[150:151], v[14:15] op_sel_hi:[0,1,1]
	v_pk_fma_f32 v[12:13], v[44:45], v[152:153], v[12:13] op_sel_hi:[0,1,1]
	ds_read_b128 v[150:153], v9 offset:608
	s_waitcnt lgkmcnt(11)
	v_pk_fma_f32 v[58:59], v[44:45], v[154:155], v[58:59] op_sel:[1,0,0] op_sel_hi:[1,1,1]
	v_pk_fma_f32 v[60:61], v[44:45], v[156:157], v[60:61] op_sel:[1,0,0] op_sel_hi:[1,1,1]
	ds_read_b128 v[154:157], v9 offset:624
	s_waitcnt vmcnt(8) lgkmcnt(11)
	v_pk_fma_f32 v[14:15], v[46:47], v[158:159], v[14:15] op_sel_hi:[0,1,1]
	v_pk_fma_f32 v[12:13], v[46:47], v[160:161], v[12:13] op_sel_hi:[0,1,1]
	ds_read_b128 v[158:161], v9 offset:640
	s_waitcnt lgkmcnt(11)
	v_pk_fma_f32 v[58:59], v[46:47], v[162:163], v[58:59] op_sel:[1,0,0] op_sel_hi:[1,1,1]
	v_pk_fma_f32 v[60:61], v[46:47], v[164:165], v[60:61] op_sel:[1,0,0] op_sel_hi:[1,1,1]
	ds_read_b128 v[162:165], v9 offset:656
	s_waitcnt lgkmcnt(11)
	v_pk_fma_f32 v[14:15], v[48:49], v[166:167], v[14:15] op_sel_hi:[0,1,1]
	v_pk_fma_f32 v[12:13], v[48:49], v[168:169], v[12:13] op_sel_hi:[0,1,1]
	ds_read_b128 v[166:169], v9 offset:672
	s_waitcnt lgkmcnt(11)
	v_pk_fma_f32 v[58:59], v[48:49], v[170:171], v[58:59] op_sel:[1,0,0] op_sel_hi:[1,1,1]
	v_pk_fma_f32 v[60:61], v[48:49], v[172:173], v[60:61] op_sel:[1,0,0] op_sel_hi:[1,1,1]
	ds_read_b128 v[170:173], v9 offset:688
	s_waitcnt vmcnt(7) lgkmcnt(11)
	v_pk_fma_f32 v[14:15], v[192:193], v[174:175], v[14:15] op_sel_hi:[0,1,1]
	v_pk_fma_f32 v[12:13], v[192:193], v[176:177], v[12:13] op_sel_hi:[0,1,1]
	ds_read_b128 v[174:177], v9 offset:704
	s_waitcnt lgkmcnt(11)
	v_pk_fma_f32 v[58:59], v[192:193], v[178:179], v[58:59] op_sel:[1,0,0] op_sel_hi:[1,1,1]
	v_pk_fma_f32 v[60:61], v[192:193], v[180:181], v[60:61] op_sel:[1,0,0] op_sel_hi:[1,1,1]
	ds_read_b128 v[178:181], v9 offset:720
	s_waitcnt lgkmcnt(11)
	v_pk_fma_f32 v[14:15], v[194:195], v[50:51], v[14:15] op_sel_hi:[0,1,1]
	v_pk_fma_f32 v[12:13], v[194:195], v[52:53], v[12:13] op_sel_hi:[0,1,1]
	ds_read_b128 v[50:53], v9 offset:736
	s_waitcnt lgkmcnt(11)
	v_pk_fma_f32 v[58:59], v[194:195], v[54:55], v[58:59] op_sel:[1,0,0] op_sel_hi:[1,1,1]
	v_pk_fma_f32 v[60:61], v[194:195], v[56:57], v[60:61] op_sel:[1,0,0] op_sel_hi:[1,1,1]
	ds_read_b128 v[54:57], v9 offset:752
	s_waitcnt vmcnt(6) lgkmcnt(11)
	v_pk_fma_f32 v[14:15], v[196:197], v[142:143], v[14:15] op_sel_hi:[0,1,1]
	v_pk_fma_f32 v[12:13], v[196:197], v[144:145], v[12:13] op_sel_hi:[0,1,1]
	ds_read_b128 v[142:145], v9 offset:768
	s_waitcnt lgkmcnt(11)
	v_pk_fma_f32 v[58:59], v[196:197], v[146:147], v[58:59] op_sel:[1,0,0] op_sel_hi:[1,1,1]
	v_pk_fma_f32 v[60:61], v[196:197], v[148:149], v[60:61] op_sel:[1,0,0] op_sel_hi:[1,1,1]
	ds_read_b128 v[146:149], v9 offset:784
	s_waitcnt lgkmcnt(11)
	v_pk_fma_f32 v[14:15], v[198:199], v[150:151], v[14:15] op_sel_hi:[0,1,1]
	v_pk_fma_f32 v[12:13], v[198:199], v[152:153], v[12:13] op_sel_hi:[0,1,1]
	ds_read_b128 v[150:153], v9 offset:800
	s_waitcnt lgkmcnt(11)
	v_pk_fma_f32 v[58:59], v[198:199], v[154:155], v[58:59] op_sel:[1,0,0] op_sel_hi:[1,1,1]
	v_pk_fma_f32 v[60:61], v[198:199], v[156:157], v[60:61] op_sel:[1,0,0] op_sel_hi:[1,1,1]
	ds_read_b128 v[154:157], v9 offset:816
	s_waitcnt vmcnt(5) lgkmcnt(11)
; __device__ __forceinline__ void hy_conv_item(const Ctx& C, int l, int c) {
;     ...
;     for (int k = 0; k < 8; ++k) { const int t = tid + NTHR * k; const f32x4* hr = (const f32x4*)(hdn + (size_t)t * 64);
;         float a0 = 0.f, a1 = 0.f, a2 = 0.f, a3 = 0.f;
; #pragma unroll 1
;         for (int j8 = 0; j8 < 16; j8 += 8) {
;         f32x4 hrow[8];
; #pragma unroll
;         for (int j4 = 0; j4 < 8; ++j4) hrow[j4] = hr[j8 + j4];
; #pragma unroll
;         for (int jj4 = 0; jj4 < 8; ++jj4) { const f32x4 hv = hrow[jj4]; const int j4 = j8 + jj4;
;             const f32x4 q0 = *(const f32x4*)(w3s + 4 * j4), q1 = *(const f32x4*)(w3s + 64 + 4 * j4), q2 = *(const f32x4*)(w3s + 128 + 4 * j4), q3 = *(const f32x4*)(w3s + 192 + 4 * j4);
;             a0 += hv.x * q0.x + hv.y * q0.y + hv.z * q0.z + hv.w * q0.w; a1 += hv.x * q1.x + hv.y * q1.y + hv.z * q1.z + hv.w * q1.w;
;             a2 += hv.x * q2.x + hv.y * q2.y + hv.z * q2.z + hv.w * q2.w; a3 += hv.x * q3.x + hv.y * q3.y + hv.z * q3.z + hv.w * q3.w; } }
;         const float dec = __expf(-((float)t / 4095.f) * adelta);
;         a0 *= dec; a1 *= dec; a2 *= dec; a3 *= dec;
;         hft[t] = a0; hft[4096 + t] = a1; hft[8192 + t] = a2; hft[12288 + t] = a3;
;         ss[0] += a0 * a0; ss[1] += a1 * a1; ss[2] += a2 * a2; ss[3] += a3 * a3; }
; #pragma unroll
;     for (int q = 0; q < 4; ++q) { const float s_ = wave_sum(ss[q]); if (lane == 0) red[w * 4 + q] = s_; }
	v_pk_fma_f32 v[14:15], v[200:201], v[158:159], v[14:15] op_sel_hi:[0,1,1]
	v_pk_fma_f32 v[12:13], v[200:201], v[160:161], v[12:13] op_sel_hi:[0,1,1]
	ds_read_b128 v[158:161], v9 offset:832
	s_waitcnt lgkmcnt(11)
	v_pk_fma_f32 v[58:59], v[200:201], v[162:163], v[58:59] op_sel:[1,0,0] op_sel_hi:[1,1,1]
	v_pk_fma_f32 v[60:61], v[200:201], v[164:165], v[60:61] op_sel:[1,0,0] op_sel_hi:[1,1,1]
	ds_read_b128 v[162:165], v9 offset:848
	s_waitcnt lgkmcnt(11)
	v_pk_fma_f32 v[14:15], v[202:203], v[166:167], v[14:15] op_sel_hi:[0,1,1]
	v_pk_fma_f32 v[12:13], v[202:203], v[168:169], v[12:13] op_sel_hi:[0,1,1]
	ds_read_b128 v[166:169], v9 offset:864
	s_waitcnt lgkmcnt(11)
	v_pk_fma_f32 v[58:59], v[202:203], v[170:171], v[58:59] op_sel:[1,0,0] op_sel_hi:[1,1,1]
	v_pk_fma_f32 v[60:61], v[202:203], v[172:173], v[60:61] op_sel:[1,0,0] op_sel_hi:[1,1,1]
	ds_read_b128 v[170:173], v9 offset:880
	s_waitcnt vmcnt(4) lgkmcnt(11)
	v_pk_fma_f32 v[14:15], v[204:205], v[174:175], v[14:15] op_sel_hi:[0,1,1]
	v_pk_fma_f32 v[12:13], v[204:205], v[176:177], v[12:13] op_sel_hi:[0,1,1]
	ds_read_b128 v[174:177], v9 offset:896
	s_waitcnt lgkmcnt(11)
	v_pk_fma_f32 v[58:59], v[204:205], v[178:179], v[58:59] op_sel:[1,0,0] op_sel_hi:[1,1,1]
	v_pk_fma_f32 v[60:61], v[204:205], v[180:181], v[60:61] op_sel:[1,0,0] op_sel_hi:[1,1,1]
	ds_read_b128 v[178:181], v9 offset:912
	s_waitcnt lgkmcnt(11)
	v_pk_fma_f32 v[14:15], v[206:207], v[50:51], v[14:15] op_sel_hi:[0,1,1]
	v_pk_fma_f32 v[12:13], v[206:207], v[52:53], v[12:13] op_sel_hi:[0,1,1]
	ds_read_b128 v[50:53], v9 offset:928
	s_waitcnt lgkmcnt(11)
	v_pk_fma_f32 v[58:59], v[206:207], v[54:55], v[58:59] op_sel:[1,0,0] op_sel_hi:[1,1,1]
	v_pk_fma_f32 v[60:61], v[206:207], v[56:57], v[60:61] op_sel:[1,0,0] op_sel_hi:[1,1,1]
	ds_read_b128 v[54:57], v9 offset:944
	s_waitcnt vmcnt(3) lgkmcnt(11)
	v_pk_fma_f32 v[14:15], v[208:209], v[142:143], v[14:15] op_sel_hi:[0,1,1]
	v_pk_fma_f32 v[12:13], v[208:209], v[144:145], v[12:13] op_sel_hi:[0,1,1]
	ds_read_b128 v[142:145], v9 offset:960
	s_waitcnt lgkmcnt(11)
	v_pk_fma_f32 v[58:59], v[208:209], v[146:147], v[58:59] op_sel:[1,0,0] op_sel_hi:[1,1,1]
	v_pk_fma_f32 v[60:61], v[208:209], v[148:149], v[60:61] op_sel:[1,0,0] op_sel_hi:[1,1,1]
	ds_read_b128 v[146:149], v9 offset:976
	s_waitcnt lgkmcnt(11)
	v_pk_fma_f32 v[14:15], v[210:211], v[150:151], v[14:15] op_sel_hi:[0,1,1]
	v_pk_fma_f32 v[12:13], v[210:211], v[152:153], v[12:13] op_sel_hi:[0,1,1]
	ds_read_b128 v[150:153], v9 offset:992
	s_waitcnt lgkmcnt(11)
	v_pk_fma_f32 v[58:59], v[210:211], v[154:155], v[58:59] op_sel:[1,0,0] op_sel_hi:[1,1,1]
	v_pk_fma_f32 v[60:61], v[210:211], v[156:157], v[60:61] op_sel:[1,0,0] op_sel_hi:[1,1,1]
	ds_read_b128 v[154:157], v9 offset:1008
	s_waitcnt vmcnt(2) lgkmcnt(11)
	v_pk_fma_f32 v[14:15], v[212:213], v[158:159], v[14:15] op_sel_hi:[0,1,1]
	v_pk_fma_f32 v[12:13], v[212:213], v[160:161], v[12:13] op_sel_hi:[0,1,1]
	s_waitcnt lgkmcnt(10)
	v_pk_fma_f32 v[58:59], v[212:213], v[162:163], v[58:59] op_sel:[1,0,0] op_sel_hi:[1,1,1]
	v_pk_fma_f32 v[60:61], v[212:213], v[164:165], v[60:61] op_sel:[1,0,0] op_sel_hi:[1,1,1]
	s_waitcnt lgkmcnt(9)
	v_pk_fma_f32 v[14:15], v[214:215], v[166:167], v[14:15] op_sel_hi:[0,1,1]
	v_pk_fma_f32 v[12:13], v[214:215], v[168:169], v[12:13] op_sel_hi:[0,1,1]
	s_waitcnt lgkmcnt(8)
	v_pk_fma_f32 v[58:59], v[214:215], v[170:171], v[58:59] op_sel:[1,0,0] op_sel_hi:[1,1,1]
	v_pk_fma_f32 v[60:61], v[214:215], v[172:173], v[60:61] op_sel:[1,0,0] op_sel_hi:[1,1,1]
	s_waitcnt vmcnt(1) lgkmcnt(7)
	v_pk_fma_f32 v[14:15], v[228:229], v[174:175], v[14:15] op_sel_hi:[0,1,1]
	v_pk_fma_f32 v[12:13], v[228:229], v[176:177], v[12:13] op_sel_hi:[0,1,1]
	s_waitcnt lgkmcnt(6)
	v_pk_fma_f32 v[58:59], v[228:229], v[178:179], v[58:59] op_sel:[1,0,0] op_sel_hi:[1,1,1]
	v_pk_fma_f32 v[60:61], v[228:229], v[180:181], v[60:61] op_sel:[1,0,0] op_sel_hi:[1,1,1]
	s_waitcnt lgkmcnt(5)
	v_pk_fma_f32 v[14:15], v[230:231], v[50:51], v[14:15] op_sel_hi:[0,1,1]
	v_pk_fma_f32 v[12:13], v[230:231], v[52:53], v[12:13] op_sel_hi:[0,1,1]
	s_waitcnt lgkmcnt(4)
	v_pk_fma_f32 v[58:59], v[230:231], v[54:55], v[58:59] op_sel:[1,0,0] op_sel_hi:[1,1,1]
	v_pk_fma_f32 v[60:61], v[230:231], v[56:57], v[60:61] op_sel:[1,0,0] op_sel_hi:[1,1,1]
	s_waitcnt vmcnt(0) lgkmcnt(3)
	v_pk_fma_f32 v[14:15], v[232:233], v[142:143], v[14:15] op_sel_hi:[0,1,1]
	v_pk_fma_f32 v[12:13], v[232:233], v[144:145], v[12:13] op_sel_hi:[0,1,1]
	s_waitcnt lgkmcnt(2)
	v_pk_fma_f32 v[58:59], v[232:233], v[146:147], v[58:59] op_sel:[1,0,0] op_sel_hi:[1,1,1]
	v_pk_fma_f32 v[60:61], v[232:233], v[148:149], v[60:61] op_sel:[1,0,0] op_sel_hi:[1,1,1]
	s_waitcnt lgkmcnt(1)
	v_pk_fma_f32 v[14:15], v[234:235], v[150:151], v[14:15] op_sel_hi:[0,1,1]
	v_pk_fma_f32 v[12:13], v[234:235], v[152:153], v[12:13] op_sel_hi:[0,1,1]
	s_waitcnt lgkmcnt(0)
	v_pk_fma_f32 v[58:59], v[234:235], v[154:155], v[58:59] op_sel:[1,0,0] op_sel_hi:[1,1,1]
	v_pk_fma_f32 v[60:61], v[234:235], v[156:157], v[60:61] op_sel:[1,0,0] op_sel_hi:[1,1,1]
	v_pk_add_f32 v[14:15], v[14:15], v[58:59]
	v_pk_add_f32 v[12:13], v[12:13], v[60:61]
	v_cvt_f32_i32_e32 v0, v8
	s_add_i32 s7, s7, 1
	s_cmp_eq_u32 s7, 8
	v_rcp_f32_e32 v1, s22
	s_nop 0
	v_mul_f32_e32 v0, v0, v1
	v_mul_f32_e32 v0, v16, v0
	v_mul_f32_e32 v0, 0x3fb8aa3b, v0
	v_exp_f32_e32 v0, v0
	v_lshl_add_u32 v1, v8, 2, 0
	v_add_u32_e32 v8, 0x11000, v1
	v_pk_mul_f32 v[2:3], v[0:1], v[14:15] op_sel_hi:[0,1]
	v_pk_mul_f32 v[0:1], v[0:1], v[12:13] op_sel_hi:[0,1]
	v_pk_fma_f32 v[6:7], v[2:3], v[2:3], v[6:7]
	v_pk_fma_f32 v[4:5], v[0:1], v[0:1], v[4:5]
	ds_write2st64_b32 v8, v2, v3 offset1:64
	ds_write2st64_b32 v8, v0, v1 offset0:128 offset1:192
	s_cbranch_scc0 .LBB0_612
	ds_bpermute_b32 v0, v64, v6
	s_waitcnt lgkmcnt(0)
	v_add_f32_e32 v0, v6, v0
	ds_bpermute_b32 v1, v130, v0
	s_waitcnt lgkmcnt(0)
	v_add_f32_e32 v0, v0, v1
	ds_bpermute_b32 v1, v131, v0
	s_waitcnt lgkmcnt(0)
	v_add_f32_e32 v0, v0, v1
	ds_bpermute_b32 v1, v132, v0
	s_waitcnt lgkmcnt(0)
	v_add_f32_e32 v0, v0, v1
	ds_bpermute_b32 v1, v133, v0
	s_waitcnt lgkmcnt(0)
	v_add_f32_e32 v0, v0, v1
	ds_bpermute_b32 v1, v134, v0
	s_and_saveexec_b64 s[0:1], s[46:47]
	s_cbranch_execz .LBB0_617
	s_add_i32 s7, s12, 0
	s_add_i32 s7, s7, 0x25080
	s_waitcnt lgkmcnt(0)
	v_add_f32_e32 v0, v0, v1
	v_mov_b32_e32 v1, s7
	ds_write_b32 v1, v0
